# MFMA/LDS interleave in attention item C: the 8 bias LDS reads are issued before the 4 QK MFMAs so their latency sits in the MFMA shadow
# speedup vs baseline: 1.0044x; 1.0044x over previous
; __device__ __forceinline__ float qmax(float x) { float a = x, b = x; swap16(a, b); a = fmaxf(a, b); b = a; swap32(a, b); return fmaxf(a, b); }
; __device__ __forceinline__ void softmax_pv(float& m, float& l, f32x4 (&o)[4], f32x4 s0, f32x4 s1, const bf16x8 (&vf)[4], float kL2e) {
;     float mx = fmaxf(fmaxf(fmaxf(s0[0], s0[1]), fmaxf(s0[2], s0[3])), fmaxf(fmaxf(s1[0], s1[1]), fmaxf(s1[2], s1[3])));
;     mx = qmax(mx);
;     const float mn = fmaxf(m, mx);
;     if (__builtin_amdgcn_ballot_w64(mn > m) != 0ull) {
;         const float alpha = __builtin_amdgcn_exp2f((m - mn) * kL2e);
;         l *= alpha;
; #pragma unroll
;         for (int dt = 0; dt < 4; ++dt) o[dt] = o[dt] * alpha;
;         m = mn;
;     }
.LBB0_516:
	v_add_u32_e32 v218, s43, v198
	v_add_u32_e32 v219, s43, v197
	v_add_u32_e32 v220, s43, v196
	v_add_u32_e32 v221, s43, v195
	v_add_u32_e32 v222, s43, v194
	v_add_u32_e32 v223, s43, v193
	v_add_u32_e32 v224, s43, v192
	v_add_u32_e32 v225, s43, v191
	s_add_i32 s48, s49, 1
	s_min_i32 s22, s48, s31
	s_add_i32 s22, s22, s1
	s_lshl_b32 s22, s22, 6
	s_add_i32 s22, s22, s30
	s_waitcnt vmcnt(3)
	v_mad_i64_i32 v[134:135], s[24:25], s22, v242, v[182:183]
	s_movk_i32 s24, 0x5000
	s_ashr_i32 s23, s22, 31
	global_load_dwordx4 v[150:153], v[134:135], off
	global_load_dwordx4 v[154:157], v[134:135], off offset:64
	v_add_co_u32_e32 v134, vcc, s24, v134
	s_waitcnt vmcnt(2)
	v_lshl_add_u64 v[142:143], s[22:23], 1, v[184:185]
	v_addc_co_u32_e32 v135, vcc, 0, v135, vcc
	v_add_co_u32_e32 v138, vcc, s45, v142
	global_load_dwordx4 v[162:165], v[134:135], off offset:2048
	global_load_dwordx4 v[158:161], v[134:135], off offset:2112
	v_addc_co_u32_e32 v139, vcc, 0, v143, vcc
	v_add_co_u32_e32 v144, vcc, 0x121000, v142
	global_load_dwordx4 v[134:137], v[142:143], off
	s_nop 0
	global_load_dwordx4 v[138:141], v[138:139], off offset:2048
	v_addc_co_u32_e32 v145, vcc, 0, v143, vcc
	v_add_co_u32_e32 v142, vcc, 0x1b1000, v142
	s_cmp_lt_u32 s49, 8
	s_nop 0
	v_addc_co_u32_e32 v143, vcc, 0, v143, vcc
	global_load_dwordx4 v[146:149], v[144:145], off
	s_nop 0
	global_load_dwordx4 v[142:145], v[142:143], off offset:2048
	s_cselect_b64 s[22:23], -1, 0
	s_cmp_gt_u32 s49, 7
	s_cbranch_scc1 .LBB0_537
	ds_read_b32 v210, v218 offset:868
	ds_read_b32 v211, v219 offset:868
	ds_read_b32 v212, v220 offset:868
	ds_read_b32 v213, v221 offset:868
	ds_read_b32 v214, v222 offset:868
	ds_read_b32 v215, v223 offset:868
	ds_read_b32 v216, v224 offset:868
	ds_read_b32 v217, v225 offset:868
	s_waitcnt vmcnt(8)
	v_mfma_f32_16x16x32_bf16 v[166:169], v[102:105], v[82:85], 0
	v_mfma_f32_16x16x32_bf16 v[170:173], v[106:109], v[78:81], v[166:169]
	v_mfma_f32_16x16x32_bf16 v[166:169], v[110:113], v[82:85], 0
	v_mfma_f32_16x16x32_bf16 v[166:169], v[114:117], v[78:81], v[166:169]
	s_waitcnt lgkmcnt(0)
	s_nop 4
	v_add_f32_e32 v210, v170, v210
	v_add_f32_e32 v212, v171, v212
	v_add_f32_e32 v214, v172, v214
	v_add_f32_e32 v216, v173, v216
	v_add_f32_e32 v211, v166, v211
	v_add_f32_e32 v213, v167, v213
	v_add_f32_e32 v215, v168, v215
	v_add_f32_e32 v217, v169, v217
	v_cndmask_b32_e64 v186, v19, v210, s[6:7]
	v_cndmask_b32_e64 v170, v19, v211, s[8:9]
	v_cndmask_b32_e64 v166, v19, v212, s[10:11]
	v_cndmask_b32_e64 v171, v19, v213, s[14:15]
	v_cndmask_b32_e64 v167, v19, v214, s[16:17]
	v_cndmask_b32_e64 v172, v19, v215, s[18:19]
	v_cndmask_b32_e64 v168, v19, v216, s[20:21]
	v_cndmask_b32_e64 v173, v19, v217, s[2:3]
	v_max_f32_e32 v169, v186, v166
	v_max_f32_e32 v187, v167, v168
	v_max_f32_e32 v203, v172, v173
	v_max3_f32 v203, v170, v171, v203
	v_max3_f32 v169, v169, v187, v203
	v_mov_b32_e32 v187, v169
	s_nop 1
	v_permlane16_swap_b32 v169, v187
	s_nop 1
	s_nop 0
	v_max_f32_e32 v169, v169, v187
	v_mov_b32_e32 v187, v169
	s_nop 1
	v_permlane32_swap_b32 v169, v187
	s_nop 1
	s_nop 0
	v_max3_f32 v187, v199, v169, v187
	v_cmp_gt_f32_e32 vcc, v187, v199
	s_cbranch_vccz .LBB0_535
	v_sub_f32_e32 v169, v199, v187
	v_mul_f32_e32 v169, v20, v169
	v_exp_f32_e32 v204, v169
	s_nop 0
	v_mul_f32_e32 v190, v190, v204
	v_pk_mul_f32 v[100:101], v[100:101], v[204:205] op_sel_hi:[1,0]
	v_pk_mul_f32 v[98:99], v[98:99], v[204:205] op_sel_hi:[1,0]
	v_pk_mul_f32 v[96:97], v[96:97], v[204:205] op_sel_hi:[1,0]
	v_pk_mul_f32 v[94:95], v[94:95], v[204:205] op_sel_hi:[1,0]
	v_pk_mul_f32 v[92:93], v[92:93], v[204:205] op_sel_hi:[1,0]
	v_pk_mul_f32 v[90:91], v[90:91], v[204:205] op_sel_hi:[1,0]
	v_pk_mul_f32 v[88:89], v[88:89], v[204:205] op_sel_hi:[1,0]
	v_pk_mul_f32 v[86:87], v[86:87], v[204:205] op_sel_hi:[1,0]
	s_branch .LBB0_536

; __device__ __forceinline__ float qmax(float x) { float a = x, b = x; swap16(a, b); a = fmaxf(a, b); b = a; swap32(a, b); return fmaxf(a, b); }
; __device__ __forceinline__ void softmax_pv(float& m, float& l, f32x4 (&o)[4], f32x4 s0, f32x4 s1, const bf16x8 (&vf)[4], float kL2e) {
;     float mx = fmaxf(fmaxf(fmaxf(s0[0], s0[1]), fmaxf(s0[2], s0[3])), fmaxf(fmaxf(s1[0], s1[1]), fmaxf(s1[2], s1[3])));
;     mx = qmax(mx);
;     const float mn = fmaxf(m, mx);
;     if (__builtin_amdgcn_ballot_w64(mn > m) != 0ull) {
;         const float alpha = __builtin_amdgcn_exp2f((m - mn) * kL2e);
;         l *= alpha;
; #pragma unroll
;         for (int dt = 0; dt < 4; ++dt) o[dt] = o[dt] * alpha;
;         m = mn;
;     }
.LBB0_537:
	s_add_i32 s50, s1, s49
	s_cmp_ge_u32 s50, s27
	s_cselect_b64 s[24:25], -1, 0
	s_cmp_lt_u32 s50, s34
	s_cselect_b64 s[56:57], -1, 0
	s_and_b64 s[24:25], s[24:25], s[56:57]
	s_andn2_b64 vcc, exec, s[24:25]
	s_cbranch_vccnz .LBB0_558
	ds_read_b32 v210, v218 offset:744
	ds_read_b32 v211, v219 offset:744
	ds_read_b32 v212, v220 offset:744
	ds_read_b32 v213, v221 offset:744
	ds_read_b32 v214, v222 offset:744
	ds_read_b32 v215, v223 offset:744
	ds_read_b32 v216, v224 offset:744
	ds_read_b32 v217, v225 offset:744
	s_waitcnt vmcnt(8)
	v_mfma_f32_16x16x32_bf16 v[166:169], v[102:105], v[74:77], 0
	v_mfma_f32_16x16x32_bf16 v[170:173], v[106:109], v[70:73], v[166:169]
	v_mfma_f32_16x16x32_bf16 v[166:169], v[110:113], v[74:77], 0
	v_mfma_f32_16x16x32_bf16 v[166:169], v[114:117], v[70:73], v[166:169]
	s_waitcnt lgkmcnt(0)
	s_nop 4
	v_add_f32_e32 v210, v170, v210
	v_add_f32_e32 v212, v171, v212
	v_add_f32_e32 v214, v172, v214
	v_add_f32_e32 v216, v173, v216
	v_add_f32_e32 v211, v166, v211
	v_add_f32_e32 v213, v167, v213
	v_add_f32_e32 v215, v168, v215
	v_add_f32_e32 v217, v169, v217
	v_cndmask_b32_e64 v186, v19, v210, s[6:7]
	v_cndmask_b32_e64 v170, v19, v211, s[8:9]
	v_cndmask_b32_e64 v166, v19, v212, s[10:11]
	v_cndmask_b32_e64 v171, v19, v213, s[14:15]
	v_cndmask_b32_e64 v167, v19, v214, s[16:17]
	v_cndmask_b32_e64 v172, v19, v215, s[18:19]
	v_cndmask_b32_e64 v168, v19, v216, s[20:21]
	v_cndmask_b32_e64 v173, v19, v217, s[2:3]
	v_max_f32_e32 v169, v186, v166
	v_max_f32_e32 v187, v167, v168
	v_max_f32_e32 v203, v172, v173
	v_max3_f32 v203, v170, v171, v203
	v_max3_f32 v169, v169, v187, v203
	v_mov_b32_e32 v187, v169
	s_nop 1
	v_permlane16_swap_b32 v169, v187
	s_nop 1
	s_nop 0
	v_max_f32_e32 v169, v169, v187
	v_mov_b32_e32 v187, v169
	s_nop 1
	v_permlane32_swap_b32 v169, v187
	s_nop 1
	s_nop 0
	v_max3_f32 v187, v200, v169, v187
	v_cmp_gt_f32_e32 vcc, v187, v200
	s_cbranch_vccz .LBB0_556
	v_sub_f32_e32 v169, v200, v187
	v_mul_f32_e32 v169, v20, v169
	v_exp_f32_e32 v200, v169
	s_nop 0
	v_mul_f32_e32 v189, v189, v200
	v_pk_mul_f32 v[68:69], v[68:69], v[200:201] op_sel_hi:[1,0]
	v_pk_mul_f32 v[66:67], v[66:67], v[200:201] op_sel_hi:[1,0]
	v_pk_mul_f32 v[56:57], v[56:57], v[200:201] op_sel_hi:[1,0]
	v_pk_mul_f32 v[54:55], v[54:55], v[200:201] op_sel_hi:[1,0]
	v_pk_mul_f32 v[48:49], v[48:49], v[200:201] op_sel_hi:[1,0]
	v_pk_mul_f32 v[46:47], v[46:47], v[200:201] op_sel_hi:[1,0]
	v_pk_mul_f32 v[40:41], v[40:41], v[200:201] op_sel_hi:[1,0]
	v_pk_mul_f32 v[38:39], v[38:39], v[200:201] op_sel_hi:[1,0]
	s_branch .LBB0_557

; __device__ __forceinline__ float qmax(float x) { float a = x, b = x; swap16(a, b); a = fmaxf(a, b); b = a; swap32(a, b); return fmaxf(a, b); }
; __device__ __forceinline__ void softmax_pv(float& m, float& l, f32x4 (&o)[4], f32x4 s0, f32x4 s1, const bf16x8 (&vf)[4], float kL2e) {
;     float mx = fmaxf(fmaxf(fmaxf(s0[0], s0[1]), fmaxf(s0[2], s0[3])), fmaxf(fmaxf(s1[0], s1[1]), fmaxf(s1[2], s1[3])));
;     mx = qmax(mx);
;     const float mn = fmaxf(m, mx);
;     if (__builtin_amdgcn_ballot_w64(mn > m) != 0ull) {
;         const float alpha = __builtin_amdgcn_exp2f((m - mn) * kL2e);
;         l *= alpha;
; #pragma unroll
;         for (int dt = 0; dt < 4; ++dt) o[dt] = o[dt] * alpha;
;         m = mn;
;     }
.LBB0_558:
	s_cmp_ge_u32 s50, s28
	s_cselect_b64 s[24:25], -1, 0
	s_cmp_lt_u32 s50, s35
	s_cselect_b64 s[56:57], -1, 0
	s_and_b64 s[24:25], s[24:25], s[56:57]
	s_andn2_b64 vcc, exec, s[24:25]
	s_cbranch_vccnz .LBB0_579
	ds_read_b32 v210, v218 offset:620
	ds_read_b32 v211, v219 offset:620
	ds_read_b32 v212, v220 offset:620
	ds_read_b32 v213, v221 offset:620
	ds_read_b32 v214, v222 offset:620
	ds_read_b32 v215, v223 offset:620
	ds_read_b32 v216, v224 offset:620
	ds_read_b32 v217, v225 offset:620
	s_waitcnt vmcnt(8)
	v_mfma_f32_16x16x32_bf16 v[166:169], v[102:105], v[62:65], 0
	v_mfma_f32_16x16x32_bf16 v[170:173], v[106:109], v[58:61], v[166:169]
	v_mfma_f32_16x16x32_bf16 v[166:169], v[110:113], v[62:65], 0
	v_mfma_f32_16x16x32_bf16 v[166:169], v[114:117], v[58:61], v[166:169]
	s_waitcnt lgkmcnt(0)
	s_nop 4
	v_add_f32_e32 v210, v170, v210
	v_add_f32_e32 v212, v171, v212
	v_add_f32_e32 v214, v172, v214
	v_add_f32_e32 v216, v173, v216
	v_add_f32_e32 v211, v166, v211
	v_add_f32_e32 v213, v167, v213
	v_add_f32_e32 v215, v168, v215
	v_add_f32_e32 v217, v169, v217
	v_cndmask_b32_e64 v186, v19, v210, s[6:7]
	v_cndmask_b32_e64 v170, v19, v211, s[8:9]
	v_cndmask_b32_e64 v166, v19, v212, s[10:11]
	v_cndmask_b32_e64 v171, v19, v213, s[14:15]
	v_cndmask_b32_e64 v167, v19, v214, s[16:17]
	v_cndmask_b32_e64 v172, v19, v215, s[18:19]
	v_cndmask_b32_e64 v168, v19, v216, s[20:21]
	v_cndmask_b32_e64 v173, v19, v217, s[2:3]
	v_max_f32_e32 v169, v186, v166
	v_max_f32_e32 v187, v167, v168
	v_max_f32_e32 v203, v172, v173
	v_max3_f32 v203, v170, v171, v203
	v_max3_f32 v169, v169, v187, v203
	v_mov_b32_e32 v187, v169
	s_nop 1
	v_permlane16_swap_b32 v187, v169
	s_nop 1
	s_nop 0
	v_max_f32_e32 v169, v187, v169
	v_mov_b32_e32 v187, v169
	s_nop 1
	v_permlane32_swap_b32 v187, v169
	s_nop 1
	s_nop 0
	v_max3_f32 v187, v201, v187, v169
	v_cmp_gt_f32_e32 vcc, v187, v201
	s_cbranch_vccz .LBB0_577
	v_sub_f32_e32 v169, v201, v187
	v_mul_f32_e32 v169, v20, v169
	v_exp_f32_e32 v204, v169
	s_nop 0
	v_mul_f32_e32 v0, v0, v204
	v_pk_mul_f32 v[36:37], v[36:37], v[204:205] op_sel_hi:[1,0]
	v_pk_mul_f32 v[34:35], v[34:35], v[204:205] op_sel_hi:[1,0]
	v_pk_mul_f32 v[32:33], v[32:33], v[204:205] op_sel_hi:[1,0]
	v_pk_mul_f32 v[30:31], v[30:31], v[204:205] op_sel_hi:[1,0]
	v_pk_mul_f32 v[28:29], v[28:29], v[204:205] op_sel_hi:[1,0]
	v_pk_mul_f32 v[26:27], v[26:27], v[204:205] op_sel_hi:[1,0]
	v_pk_mul_f32 v[24:25], v[24:25], v[204:205] op_sel_hi:[1,0]
	v_pk_mul_f32 v[22:23], v[22:23], v[204:205] op_sel_hi:[1,0]
	s_branch .LBB0_578

; __device__ __forceinline__ float qmax(float x) { float a = x, b = x; swap16(a, b); a = fmaxf(a, b); b = a; swap32(a, b); return fmaxf(a, b); }
; __device__ __forceinline__ void softmax_pv(float& m, float& l, f32x4 (&o)[4], f32x4 s0, f32x4 s1, const bf16x8 (&vf)[4], float kL2e) {
;     float mx = fmaxf(fmaxf(fmaxf(s0[0], s0[1]), fmaxf(s0[2], s0[3])), fmaxf(fmaxf(s1[0], s1[1]), fmaxf(s1[2], s1[3])));
;     mx = qmax(mx);
;     const float mn = fmaxf(m, mx);
;     if (__builtin_amdgcn_ballot_w64(mn > m) != 0ull) {
;         const float alpha = __builtin_amdgcn_exp2f((m - mn) * kL2e);
;         l *= alpha;
; #pragma unroll
;         for (int dt = 0; dt < 4; ++dt) o[dt] = o[dt] * alpha;
;         m = mn;
;     }
.LBB0_579:
	s_cmp_ge_u32 s50, s26
	s_cselect_b64 s[24:25], -1, 0
	s_cmp_lt_u32 s50, s42
	s_cselect_b64 s[56:57], -1, 0
	s_and_b64 s[24:25], s[24:25], s[56:57]
	s_andn2_b64 vcc, exec, s[24:25]
	s_cbranch_vccnz .LBB0_600
	ds_read_b32 v210, v218 offset:496
	ds_read_b32 v211, v219 offset:496
	ds_read_b32 v212, v220 offset:496
	ds_read_b32 v213, v221 offset:496
	ds_read_b32 v214, v222 offset:496
	ds_read_b32 v215, v223 offset:496
	ds_read_b32 v216, v224 offset:496
	ds_read_b32 v217, v225 offset:496
	s_waitcnt vmcnt(8)
	v_mfma_f32_16x16x32_bf16 v[166:169], v[102:105], v[50:53], 0
	v_mfma_f32_16x16x32_bf16 v[170:173], v[106:109], v[42:45], v[166:169]
	v_mfma_f32_16x16x32_bf16 v[166:169], v[110:113], v[50:53], 0
	v_mfma_f32_16x16x32_bf16 v[166:169], v[114:117], v[42:45], v[166:169]
	s_waitcnt lgkmcnt(0)
	s_nop 4
	v_add_f32_e32 v210, v170, v210
	v_add_f32_e32 v212, v171, v212
	v_add_f32_e32 v214, v172, v214
	v_add_f32_e32 v216, v173, v216
	v_add_f32_e32 v211, v166, v211
	v_add_f32_e32 v213, v167, v213
	v_add_f32_e32 v215, v168, v215
	v_add_f32_e32 v217, v169, v217
	v_cndmask_b32_e64 v186, v19, v210, s[6:7]
	v_cndmask_b32_e64 v170, v19, v211, s[8:9]
	v_cndmask_b32_e64 v166, v19, v212, s[10:11]
	v_cndmask_b32_e64 v171, v19, v213, s[14:15]
	v_cndmask_b32_e64 v167, v19, v214, s[16:17]
	v_cndmask_b32_e64 v172, v19, v215, s[18:19]
	v_cndmask_b32_e64 v168, v19, v216, s[20:21]
	v_cndmask_b32_e64 v173, v19, v217, s[2:3]
	v_max_f32_e32 v169, v186, v166
	v_max_f32_e32 v187, v167, v168
	v_max_f32_e32 v203, v172, v173
	v_max3_f32 v203, v170, v171, v203
	v_max3_f32 v169, v169, v187, v203
	v_mov_b32_e32 v187, v169
	s_nop 1
	v_permlane16_swap_b32 v169, v187
	s_nop 1
	s_nop 0
	v_max_f32_e32 v169, v169, v187
	v_mov_b32_e32 v187, v169
	s_nop 1
	v_permlane32_swap_b32 v169, v187
	s_nop 1
	s_nop 0
	v_max3_f32 v187, v202, v169, v187
	v_cmp_gt_f32_e32 vcc, v187, v202
	s_cbranch_vccz .LBB0_598
	v_sub_f32_e32 v169, v202, v187
	v_mul_f32_e32 v169, v20, v169
	v_exp_f32_e32 v202, v169
	s_nop 0
	v_mul_f32_e32 v18, v18, v202
	v_pk_mul_f32 v[16:17], v[16:17], v[202:203] op_sel_hi:[1,0]
	v_pk_mul_f32 v[14:15], v[14:15], v[202:203] op_sel_hi:[1,0]
	v_pk_mul_f32 v[12:13], v[12:13], v[202:203] op_sel_hi:[1,0]
	v_pk_mul_f32 v[10:11], v[10:11], v[202:203] op_sel_hi:[1,0]
	v_pk_mul_f32 v[8:9], v[8:9], v[202:203] op_sel_hi:[1,0]
	v_pk_mul_f32 v[6:7], v[6:7], v[202:203] op_sel_hi:[1,0]
	v_pk_mul_f32 v[4:5], v[4:5], v[202:203] op_sel_hi:[1,0]
	v_pk_mul_f32 v[2:3], v[2:3], v[202:203] op_sel_hi:[1,0]
	s_branch .LBB0_599

; __device__ __forceinline__ float qmax(float x) { float a = x, b = x; swap16(a, b); a = fmaxf(a, b); b = a; swap32(a, b); return fmaxf(a, b); }
; __device__ __forceinline__ void softmax_pv(float& m, float& l, f32x4 (&o)[4], f32x4 s0, f32x4 s1, const bf16x8 (&vf)[4], float kL2e) {
;     float mx = fmaxf(fmaxf(fmaxf(s0[0], s0[1]), fmaxf(s0[2], s0[3])), fmaxf(fmaxf(s1[0], s1[1]), fmaxf(s1[2], s1[3])));
;     mx = qmax(mx);
;     const float mn = fmaxf(m, mx);
;     if (__builtin_amdgcn_ballot_w64(mn > m) != 0ull) {
;         const float alpha = __builtin_amdgcn_exp2f((m - mn) * kL2e);
;         l *= alpha;
; #pragma unroll
;         for (int dt = 0; dt < 4; ++dt) o[dt] = o[dt] * alpha;
;         m = mn;
;     }
.LBB0_600:
	s_cmp_ge_i32 s48, s29
	s_cbranch_scc1 .LBB0_515
	s_add_i32 s24, s49, 2
	s_min_i32 s24, s24, s31
	s_add_i32 s24, s24, s1
	s_lshl_b32 s24, s24, 6
	s_add_i32 s24, s24, s30
	s_waitcnt vmcnt(10)
	v_mad_i64_i32 v[110:111], s[56:57], s24, v242, v[182:183]
	s_ashr_i32 s25, s24, 31
	v_add_co_u32_e32 v114, vcc, 0x5000, v110
	v_lshl_add_u64 v[126:127], s[24:25], 1, v[184:185]
	s_nop 0
	v_addc_co_u32_e32 v115, vcc, 0, v111, vcc
	v_add_co_u32_e32 v122, vcc, 0x90000, v126
	global_load_dwordx4 v[102:105], v[110:111], off
	global_load_dwordx4 v[106:109], v[110:111], off offset:64
	v_addc_co_u32_e32 v123, vcc, 0, v127, vcc
	v_add_co_u32_e32 v128, vcc, 0x121000, v126
	global_load_dwordx4 v[110:113], v[114:115], off offset:2048
	s_nop 0
	global_load_dwordx4 v[114:117], v[114:115], off offset:2112
	v_addc_co_u32_e32 v129, vcc, 0, v127, vcc
	v_add_co_u32_e32 v130, vcc, 0x1b1000, v126
	global_load_dwordx4 v[118:121], v[126:127], off
	s_nop 0
	global_load_dwordx4 v[122:125], v[122:123], off offset:2048
	v_addc_co_u32_e32 v131, vcc, 0, v127, vcc
	global_load_dwordx4 v[126:129], v[128:129], off
	s_nop 0
	global_load_dwordx4 v[130:133], v[130:131], off offset:2048
	s_andn2_b64 vcc, exec, s[22:23]
	s_cbranch_vccnz .LBB0_623
	ds_read_b32 v210, v218 offset:992
	ds_read_b32 v211, v219 offset:992
	ds_read_b32 v212, v220 offset:992
	ds_read_b32 v213, v221 offset:992
	ds_read_b32 v214, v222 offset:992
	ds_read_b32 v215, v223 offset:992
	ds_read_b32 v216, v224 offset:992
	ds_read_b32 v217, v225 offset:992
	s_waitcnt vmcnt(15)
	v_mfma_f32_16x16x32_bf16 v[166:169], v[150:153], v[82:85], 0
	s_waitcnt vmcnt(14)
	v_mfma_f32_16x16x32_bf16 v[170:173], v[154:157], v[78:81], v[166:169]
	s_waitcnt vmcnt(13)
	v_mfma_f32_16x16x32_bf16 v[166:169], v[162:165], v[82:85], 0
	s_waitcnt vmcnt(12)
	v_mfma_f32_16x16x32_bf16 v[166:169], v[158:161], v[78:81], v[166:169]
	s_waitcnt lgkmcnt(0)
	s_nop 4
	v_add_f32_e32 v210, v170, v210
	v_add_f32_e32 v212, v171, v212
	v_add_f32_e32 v214, v172, v214
	v_add_f32_e32 v216, v173, v216
	v_add_f32_e32 v211, v166, v211
	v_add_f32_e32 v213, v167, v213
	v_add_f32_e32 v215, v168, v215
	v_add_f32_e32 v217, v169, v217
	v_cndmask_b32_e64 v186, v19, v210, s[6:7]
	v_cndmask_b32_e64 v170, v19, v211, s[8:9]
	v_cndmask_b32_e64 v166, v19, v212, s[10:11]
	v_cndmask_b32_e64 v171, v19, v213, s[14:15]
	v_cndmask_b32_e64 v167, v19, v214, s[16:17]
	v_cndmask_b32_e64 v172, v19, v215, s[18:19]
	v_cndmask_b32_e64 v168, v19, v216, s[20:21]
	v_cndmask_b32_e64 v173, v19, v217, s[2:3]
	v_max_f32_e32 v169, v186, v166
	v_max_f32_e32 v187, v167, v168
	v_max_f32_e32 v203, v172, v173
	v_max3_f32 v203, v170, v171, v203
	v_max3_f32 v169, v169, v187, v203
	v_mov_b32_e32 v187, v169
	s_nop 1
	v_permlane16_swap_b32 v169, v187
	s_nop 1
	s_nop 0
	v_max_f32_e32 v169, v169, v187
	v_mov_b32_e32 v187, v169
	s_nop 1
	v_permlane32_swap_b32 v169, v187
	s_nop 1
	s_nop 0
	v_max3_f32 v187, v199, v169, v187
	v_cmp_gt_f32_e32 vcc, v187, v199
	s_cbranch_vccz .LBB0_621
	v_sub_f32_e32 v169, v199, v187
	v_mul_f32_e32 v169, v20, v169
	v_exp_f32_e32 v204, v169
	s_nop 0
	v_mul_f32_e32 v190, v190, v204
	v_pk_mul_f32 v[100:101], v[100:101], v[204:205] op_sel_hi:[1,0]
	v_pk_mul_f32 v[98:99], v[98:99], v[204:205] op_sel_hi:[1,0]
	v_pk_mul_f32 v[96:97], v[96:97], v[204:205] op_sel_hi:[1,0]
	v_pk_mul_f32 v[94:95], v[94:95], v[204:205] op_sel_hi:[1,0]
	v_pk_mul_f32 v[92:93], v[92:93], v[204:205] op_sel_hi:[1,0]
	v_pk_mul_f32 v[90:91], v[90:91], v[204:205] op_sel_hi:[1,0]
	v_pk_mul_f32 v[88:89], v[88:89], v[204:205] op_sel_hi:[1,0]
	v_pk_mul_f32 v[86:87], v[86:87], v[204:205] op_sel_hi:[1,0]
	s_branch .LBB0_622

; __device__ __forceinline__ float qmax(float x) { float a = x, b = x; swap16(a, b); a = fmaxf(a, b); b = a; swap32(a, b); return fmaxf(a, b); }
; __device__ __forceinline__ void softmax_pv(float& m, float& l, f32x4 (&o)[4], f32x4 s0, f32x4 s1, const bf16x8 (&vf)[4], float kL2e) {
;     float mx = fmaxf(fmaxf(fmaxf(s0[0], s0[1]), fmaxf(s0[2], s0[3])), fmaxf(fmaxf(s1[0], s1[1]), fmaxf(s1[2], s1[3])));
;     mx = qmax(mx);
;     const float mn = fmaxf(m, mx);
;     if (__builtin_amdgcn_ballot_w64(mn > m) != 0ull) {
;         const float alpha = __builtin_amdgcn_exp2f((m - mn) * kL2e);
;         l *= alpha;
; #pragma unroll
;         for (int dt = 0; dt < 4; ++dt) o[dt] = o[dt] * alpha;
;         m = mn;
;     }
.LBB0_623:
	s_add_i32 s50, s50, 1
	s_cmp_ge_u32 s50, s27
	s_cselect_b64 s[22:23], -1, 0
	s_cmp_lt_u32 s50, s34
	s_cselect_b64 s[24:25], -1, 0
	s_and_b64 s[22:23], s[22:23], s[24:25]
	s_andn2_b64 vcc, exec, s[22:23]
	s_cbranch_vccnz .LBB0_644
	ds_read_b32 v210, v218 offset:868
	ds_read_b32 v211, v219 offset:868
	ds_read_b32 v212, v220 offset:868
	ds_read_b32 v213, v221 offset:868
	ds_read_b32 v214, v222 offset:868
	ds_read_b32 v215, v223 offset:868
	ds_read_b32 v216, v224 offset:868
	ds_read_b32 v217, v225 offset:868
	s_waitcnt vmcnt(15)
	v_mfma_f32_16x16x32_bf16 v[166:169], v[150:153], v[74:77], 0
	s_waitcnt vmcnt(14)
	v_mfma_f32_16x16x32_bf16 v[170:173], v[154:157], v[70:73], v[166:169]
	s_waitcnt vmcnt(13)
	v_mfma_f32_16x16x32_bf16 v[166:169], v[162:165], v[74:77], 0
	s_waitcnt vmcnt(12)
	v_mfma_f32_16x16x32_bf16 v[166:169], v[158:161], v[70:73], v[166:169]
	s_waitcnt lgkmcnt(0)
	s_nop 4
	v_add_f32_e32 v210, v170, v210
	v_add_f32_e32 v212, v171, v212
	v_add_f32_e32 v214, v172, v214
	v_add_f32_e32 v216, v173, v216
	v_add_f32_e32 v211, v166, v211
	v_add_f32_e32 v213, v167, v213
	v_add_f32_e32 v215, v168, v215
	v_add_f32_e32 v217, v169, v217
	v_cndmask_b32_e64 v186, v19, v210, s[6:7]
	v_cndmask_b32_e64 v170, v19, v211, s[8:9]
	v_cndmask_b32_e64 v166, v19, v212, s[10:11]
	v_cndmask_b32_e64 v171, v19, v213, s[14:15]
	v_cndmask_b32_e64 v167, v19, v214, s[16:17]
	v_cndmask_b32_e64 v172, v19, v215, s[18:19]
	v_cndmask_b32_e64 v168, v19, v216, s[20:21]
	v_cndmask_b32_e64 v173, v19, v217, s[2:3]
	v_max_f32_e32 v169, v186, v166
	v_max_f32_e32 v187, v167, v168
	v_max_f32_e32 v203, v172, v173
	v_max3_f32 v203, v170, v171, v203
	v_max3_f32 v169, v169, v187, v203
	v_mov_b32_e32 v187, v169
	s_nop 1
	v_permlane16_swap_b32 v169, v187
	s_nop 1
	s_nop 0
	v_max_f32_e32 v169, v169, v187
	v_mov_b32_e32 v187, v169
	s_nop 1
	v_permlane32_swap_b32 v169, v187
	s_nop 1
	s_nop 0
	v_max3_f32 v187, v200, v169, v187
	v_cmp_gt_f32_e32 vcc, v187, v200
	s_cbranch_vccz .LBB0_642
	v_sub_f32_e32 v169, v200, v187
	v_mul_f32_e32 v169, v20, v169
	v_exp_f32_e32 v200, v169
	s_nop 0
	v_mul_f32_e32 v189, v189, v200
	v_pk_mul_f32 v[68:69], v[68:69], v[200:201] op_sel_hi:[1,0]
	v_pk_mul_f32 v[66:67], v[66:67], v[200:201] op_sel_hi:[1,0]
	v_pk_mul_f32 v[56:57], v[56:57], v[200:201] op_sel_hi:[1,0]
	v_pk_mul_f32 v[54:55], v[54:55], v[200:201] op_sel_hi:[1,0]
	v_pk_mul_f32 v[48:49], v[48:49], v[200:201] op_sel_hi:[1,0]
	v_pk_mul_f32 v[46:47], v[46:47], v[200:201] op_sel_hi:[1,0]
	v_pk_mul_f32 v[40:41], v[40:41], v[200:201] op_sel_hi:[1,0]
	v_pk_mul_f32 v[38:39], v[38:39], v[200:201] op_sel_hi:[1,0]
	s_branch .LBB0_643

; __device__ __forceinline__ float qmax(float x) { float a = x, b = x; swap16(a, b); a = fmaxf(a, b); b = a; swap32(a, b); return fmaxf(a, b); }
; __device__ __forceinline__ void softmax_pv(float& m, float& l, f32x4 (&o)[4], f32x4 s0, f32x4 s1, const bf16x8 (&vf)[4], float kL2e) {
;     float mx = fmaxf(fmaxf(fmaxf(s0[0], s0[1]), fmaxf(s0[2], s0[3])), fmaxf(fmaxf(s1[0], s1[1]), fmaxf(s1[2], s1[3])));
;     mx = qmax(mx);
;     const float mn = fmaxf(m, mx);
;     if (__builtin_amdgcn_ballot_w64(mn > m) != 0ull) {
;         const float alpha = __builtin_amdgcn_exp2f((m - mn) * kL2e);
;         l *= alpha;
; #pragma unroll
;         for (int dt = 0; dt < 4; ++dt) o[dt] = o[dt] * alpha;
;         m = mn;
;     }
.LBB0_644:
	s_cmp_ge_u32 s50, s28
	s_cselect_b64 s[22:23], -1, 0
	s_cmp_lt_u32 s50, s35
	s_cselect_b64 s[24:25], -1, 0
	s_and_b64 s[22:23], s[22:23], s[24:25]
	s_andn2_b64 vcc, exec, s[22:23]
	s_cbranch_vccnz .LBB0_665
	ds_read_b32 v210, v218 offset:744
	ds_read_b32 v211, v219 offset:744
	ds_read_b32 v212, v220 offset:744
	ds_read_b32 v213, v221 offset:744
	ds_read_b32 v214, v222 offset:744
	ds_read_b32 v215, v223 offset:744
	ds_read_b32 v216, v224 offset:744
	ds_read_b32 v217, v225 offset:744
	s_waitcnt vmcnt(15)
	v_mfma_f32_16x16x32_bf16 v[166:169], v[150:153], v[62:65], 0
	s_waitcnt vmcnt(14)
	v_mfma_f32_16x16x32_bf16 v[170:173], v[154:157], v[58:61], v[166:169]
	s_waitcnt vmcnt(13)
	v_mfma_f32_16x16x32_bf16 v[166:169], v[162:165], v[62:65], 0
	s_waitcnt vmcnt(12)
	v_mfma_f32_16x16x32_bf16 v[166:169], v[158:161], v[58:61], v[166:169]
	s_waitcnt lgkmcnt(0)
	s_nop 4
	v_add_f32_e32 v210, v170, v210
	v_add_f32_e32 v212, v171, v212
	v_add_f32_e32 v214, v172, v214
	v_add_f32_e32 v216, v173, v216
	v_add_f32_e32 v211, v166, v211
	v_add_f32_e32 v213, v167, v213
	v_add_f32_e32 v215, v168, v215
	v_add_f32_e32 v217, v169, v217
	v_cndmask_b32_e64 v186, v19, v210, s[6:7]
	v_cndmask_b32_e64 v170, v19, v211, s[8:9]
	v_cndmask_b32_e64 v166, v19, v212, s[10:11]
	v_cndmask_b32_e64 v171, v19, v213, s[14:15]
	v_cndmask_b32_e64 v167, v19, v214, s[16:17]
	v_cndmask_b32_e64 v172, v19, v215, s[18:19]
	v_cndmask_b32_e64 v168, v19, v216, s[20:21]
	v_cndmask_b32_e64 v173, v19, v217, s[2:3]
	v_max_f32_e32 v169, v186, v166
	v_max_f32_e32 v187, v167, v168
	v_max_f32_e32 v203, v172, v173
	v_max3_f32 v203, v170, v171, v203
	v_max3_f32 v169, v169, v187, v203
	v_mov_b32_e32 v187, v169
	s_nop 1
	v_permlane16_swap_b32 v169, v187
	s_nop 1
	s_nop 0
	v_max_f32_e32 v169, v169, v187
	v_mov_b32_e32 v187, v169
	s_nop 1
	v_permlane32_swap_b32 v169, v187
	s_nop 1
	s_nop 0
	v_max3_f32 v187, v201, v169, v187
	v_cmp_gt_f32_e32 vcc, v187, v201
	s_cbranch_vccz .LBB0_663
	v_sub_f32_e32 v169, v201, v187
	v_mul_f32_e32 v169, v20, v169
	v_exp_f32_e32 v204, v169
	s_nop 0
	v_mul_f32_e32 v0, v0, v204
	v_pk_mul_f32 v[36:37], v[36:37], v[204:205] op_sel_hi:[1,0]
	v_pk_mul_f32 v[34:35], v[34:35], v[204:205] op_sel_hi:[1,0]
	v_pk_mul_f32 v[32:33], v[32:33], v[204:205] op_sel_hi:[1,0]
	v_pk_mul_f32 v[30:31], v[30:31], v[204:205] op_sel_hi:[1,0]
	v_pk_mul_f32 v[28:29], v[28:29], v[204:205] op_sel_hi:[1,0]
	v_pk_mul_f32 v[26:27], v[26:27], v[204:205] op_sel_hi:[1,0]
	v_pk_mul_f32 v[24:25], v[24:25], v[204:205] op_sel_hi:[1,0]
	v_pk_mul_f32 v[22:23], v[22:23], v[204:205] op_sel_hi:[1,0]
	s_branch .LBB0_664

.LBB0_665:
	s_cmp_lt_u32 s50, s26
	s_cbranch_scc1 .LBB0_515
	ds_read_b32 v210, v218 offset:620
	ds_read_b32 v211, v219 offset:620
	ds_read_b32 v212, v220 offset:620
	ds_read_b32 v213, v221 offset:620
	ds_read_b32 v214, v222 offset:620
	ds_read_b32 v215, v223 offset:620
	ds_read_b32 v216, v224 offset:620
	ds_read_b32 v217, v225 offset:620
	s_waitcnt vmcnt(15)
	v_mfma_f32_16x16x32_bf16 v[150:153], v[150:153], v[50:53], 0
	s_waitcnt vmcnt(14)
	v_mfma_f32_16x16x32_bf16 v[154:157], v[154:157], v[42:45], v[150:153]
	s_waitcnt vmcnt(13)
	v_mfma_f32_16x16x32_bf16 v[150:153], v[162:165], v[50:53], 0
	s_waitcnt vmcnt(12)
	v_mfma_f32_16x16x32_bf16 v[150:153], v[158:161], v[42:45], v[150:153]
	s_waitcnt lgkmcnt(0)
	s_nop 4
	v_add_f32_e32 v210, v154, v210
	v_add_f32_e32 v212, v155, v212
	v_add_f32_e32 v214, v156, v214
	v_add_f32_e32 v216, v157, v216
	v_add_f32_e32 v211, v150, v211
	v_add_f32_e32 v213, v151, v213
	v_add_f32_e32 v215, v152, v215
	v_add_f32_e32 v217, v153, v217
	v_cndmask_b32_e64 v162, v19, v210, s[6:7]
	v_cndmask_b32_e64 v154, v19, v211, s[8:9]
	v_cndmask_b32_e64 v150, v19, v212, s[10:11]
	v_cndmask_b32_e64 v155, v19, v213, s[14:15]
	v_cndmask_b32_e64 v151, v19, v214, s[16:17]
	v_cndmask_b32_e64 v156, v19, v215, s[18:19]
	v_cndmask_b32_e64 v152, v19, v216, s[20:21]
	v_cndmask_b32_e64 v157, v19, v217, s[2:3]
	s_branch .LBB0_512
